# last RES phase (19) no longer writes the unread bf16 copy of the residual stream
# speedup vs baseline: 1.1568x; 1.0060x over previous
; template <int EPI> ...
;     ...
;     } else if (EPI == EPI_RES) {
; #pragma unroll
;       for (int i = 0; i < 16; i++) {
;         const int rl = rbase + (i & 3) + 8 * (i >> 2);
;         const int row = m0 + rl;
;         float v0 = acc0[i], v1 = acc1[i];
;         xf[(size_t)row * 1024 + c0] = v0;
;         xf[(size_t)row * 1024 + c1] = v1;
;         outb[(size_t)row * 1024 + c0] = f2bf(v0);
;         outb[(size_t)row * 1024 + c1] = f2bf(v1);
;         float s = hsum32(v0 * v0 + v1 * v1);
;         if ((lane & 31) == 0) part[(size_t)row * 16 + nt * 2 + wn] = s;
;       }
; template <int EPI>
; __device__ __forceinline__ void gemm_phase(const Params& p, const u16* __restrict__ A, int lda, const u16* __restrict__ BT, int ldb,
;                            int K, int N, u16* __restrict__ outb, int ldo, int resid_in, int boff) {
;     ...
;     if (EPI == EPI_RES && !part_unit) {
;       const int cc0 = n0 + wn * 64 + (lane & 31);
;       float* xfq = p.out;
; #pragma unroll
;       for (int i = 0; i < 16; i++) {
;         const int row = m0 + wm * 64 + 4 * (lane >> 5) + (i & 3) + 8 * (i >> 2);
;         const float* ra = resid_in ? xrow(p, row) : (xfq + (size_t)row * 1024);
;         const float* rb = resid_in ? xrow(p, row + 32) : (xfq + (size_t)(row + 32) * 1024);
;         acc00[i] = ra[cc0]; acc01[i] = ra[cc0 + 32];
;         acc10[i] = rb[cc0]; acc11[i] = rb[cc0 + 32];
;       }
.Lgc_epi_res:
	s_lshl_b32 s11, s6, 8
	s_lshl_b32 s12, s4, 6
	s_add_u32 s11, s11, s12
	v_add_u32_e32 v238, s11, v248
	v_lshlrev_b32_e32 v243, 12, v238
	s_lshl_b32 s11, s7, 7
	v_lshl_add_u32 v239, v249, 2, s11
	v_lshlrev_b32_e32 v239, 2, v239
	v_add_u32_e32 v243, v243, v239
	v_add_u32_e32 v244, 0x10000, v243
	v_add_u32_e32 v245, 0x10000, v244
	v_add_u32_e32 v246, 0x10000, v245
	v_lshlrev_b32_e32 v247, 6, v238
	s_lshl_b32 s11, s7, 3
	v_add_u32_e32 v247, s11, v247
	s_lshl_b32 s11, s6, 8
	s_lshl_b32 s12, s4, 6
	s_add_u32 s11, s11, s12
	v_add_u32_e32 v238, s11, v248
	v_mul_lo_u32 v230, v238, s24
	s_lshl_b32 s11, s7, 7
	v_and_b32_e32 v239, 1, v249
	v_lshrrev_b32_e32 v240, 1, v249
	v_lshlrev_b32_e32 v239, 4, v239
	v_lshl_add_u32 v239, v240, 3, v239
	v_add_u32_e32 v239, s11, v239
	v_lshlrev_b32_e32 v239, 1, v239
	v_add_u32_e32 v230, v230, v239
	s_lshl_b32 s11, s24, 4
	v_add_u32_e32 v231, s11, v230
	v_add_u32_e32 v232, s11, v231
	v_add_u32_e32 v233, s11, v232
	global_load_dwordx4 v[130:133], v243, s[48:49]
	global_load_dwordx4 v[134:137], v243, s[48:49] offset:64
	global_load_dwordx4 v[138:141], v243, s[48:49] offset:128
	global_load_dwordx4 v[142:145], v243, s[48:49] offset:192
	global_load_dwordx4 v[146:149], v243, s[48:49] offset:256
	global_load_dwordx4 v[150:153], v243, s[48:49] offset:320
	global_load_dwordx4 v[154:157], v243, s[48:49] offset:384
	global_load_dwordx4 v[158:161], v243, s[48:49] offset:448
	global_load_dwordx4 v[162:165], v244, s[48:49]
	global_load_dwordx4 v[166:169], v244, s[48:49] offset:64
	global_load_dwordx4 v[170:173], v244, s[48:49] offset:128
	global_load_dwordx4 v[174:177], v244, s[48:49] offset:192
	global_load_dwordx4 v[178:181], v244, s[48:49] offset:256
	global_load_dwordx4 v[182:185], v244, s[48:49] offset:320
	global_load_dwordx4 v[186:189], v244, s[48:49] offset:384
	global_load_dwordx4 v[190:193], v244, s[48:49] offset:448
	global_load_dwordx4 v[194:197], v245, s[48:49]
	global_load_dwordx4 v[198:201], v245, s[48:49] offset:64
	global_load_dwordx4 v[202:205], v245, s[48:49] offset:128
	global_load_dwordx4 v[206:209], v245, s[48:49] offset:192
	global_load_dwordx4 v[210:213], v245, s[48:49] offset:256
	global_load_dwordx4 v[214:217], v245, s[48:49] offset:320
	global_load_dwordx4 v[218:221], v245, s[48:49] offset:384
	global_load_dwordx4 v[222:225], v245, s[48:49] offset:448
	s_waitcnt vmcnt(23)
	v_add_f32_e32 v0, v0, v130
	v_add_f32_e32 v1, v1, v131
	v_add_f32_e32 v2, v2, v132
	v_add_f32_e32 v3, v3, v133
	global_load_dwordx4 v[130:133], v246, s[48:49]
	s_waitcnt vmcnt(23)
	v_add_f32_e32 v4, v4, v134
	v_add_f32_e32 v5, v5, v135
	v_add_f32_e32 v6, v6, v136
	v_add_f32_e32 v7, v7, v137
	global_load_dwordx4 v[134:137], v246, s[48:49] offset:64
	s_waitcnt vmcnt(23)
	v_add_f32_e32 v8, v8, v138
	v_add_f32_e32 v9, v9, v139
	v_add_f32_e32 v10, v10, v140
	v_add_f32_e32 v11, v11, v141
	global_load_dwordx4 v[138:141], v246, s[48:49] offset:128
	s_waitcnt vmcnt(23)
	v_add_f32_e32 v12, v12, v142
	v_add_f32_e32 v13, v13, v143
	v_add_f32_e32 v14, v14, v144
	v_add_f32_e32 v15, v15, v145
	global_load_dwordx4 v[142:145], v246, s[48:49] offset:192
	s_waitcnt vmcnt(23)
	v_add_f32_e32 v16, v16, v146
	v_add_f32_e32 v17, v17, v147
	v_add_f32_e32 v18, v18, v148
	v_add_f32_e32 v19, v19, v149
	global_load_dwordx4 v[146:149], v246, s[48:49] offset:256
	s_waitcnt vmcnt(23)
	v_add_f32_e32 v20, v20, v150
	v_add_f32_e32 v21, v21, v151
	v_add_f32_e32 v22, v22, v152
	v_add_f32_e32 v23, v23, v153
	global_load_dwordx4 v[150:153], v246, s[48:49] offset:320
	s_waitcnt vmcnt(23)
	v_add_f32_e32 v24, v24, v154
	v_add_f32_e32 v25, v25, v155
	v_add_f32_e32 v26, v26, v156
	v_add_f32_e32 v27, v27, v157
	global_load_dwordx4 v[154:157], v246, s[48:49] offset:384
	s_waitcnt vmcnt(23)
	v_add_f32_e32 v28, v28, v158
	v_add_f32_e32 v29, v29, v159
	v_add_f32_e32 v30, v30, v160
	v_add_f32_e32 v31, v31, v161
	global_load_dwordx4 v[158:161], v246, s[48:49] offset:448
	s_waitcnt vmcnt(23)
	v_add_f32_e32 v32, v32, v162
	v_add_f32_e32 v33, v33, v163
	v_add_f32_e32 v34, v34, v164
	v_add_f32_e32 v35, v35, v165
	s_waitcnt vmcnt(22)
	v_add_f32_e32 v36, v36, v166
	v_add_f32_e32 v37, v37, v167
	v_add_f32_e32 v38, v38, v168
	v_add_f32_e32 v39, v39, v169
	s_waitcnt vmcnt(21)
	v_add_f32_e32 v40, v40, v170
	v_add_f32_e32 v41, v41, v171
	v_add_f32_e32 v42, v42, v172
	v_add_f32_e32 v43, v43, v173
	s_waitcnt vmcnt(20)
	v_add_f32_e32 v44, v44, v174
	v_add_f32_e32 v45, v45, v175
	v_add_f32_e32 v46, v46, v176
	v_add_f32_e32 v47, v47, v177
	s_waitcnt vmcnt(19)
	v_add_f32_e32 v48, v48, v178
	v_add_f32_e32 v49, v49, v179
	v_add_f32_e32 v50, v50, v180
	v_add_f32_e32 v51, v51, v181
	s_waitcnt vmcnt(18)
	v_add_f32_e32 v52, v52, v182
	v_add_f32_e32 v53, v53, v183
	v_add_f32_e32 v54, v54, v184
	v_add_f32_e32 v55, v55, v185
	s_waitcnt vmcnt(17)
	v_add_f32_e32 v56, v56, v186
	v_add_f32_e32 v57, v57, v187
	v_add_f32_e32 v58, v58, v188
	v_add_f32_e32 v59, v59, v189
	s_waitcnt vmcnt(16)
	v_add_f32_e32 v60, v60, v190
	v_add_f32_e32 v61, v61, v191
	v_add_f32_e32 v62, v62, v192
	v_add_f32_e32 v63, v63, v193
	s_waitcnt vmcnt(15)
	v_add_f32_e32 v64, v64, v194
	v_add_f32_e32 v65, v65, v195
	v_add_f32_e32 v66, v66, v196
	v_add_f32_e32 v67, v67, v197
	s_waitcnt vmcnt(14)
	v_add_f32_e32 v68, v68, v198
	v_add_f32_e32 v69, v69, v199
	v_add_f32_e32 v70, v70, v200
	v_add_f32_e32 v71, v71, v201
	s_waitcnt vmcnt(13)
	v_add_f32_e32 v72, v72, v202
	v_add_f32_e32 v73, v73, v203
	v_add_f32_e32 v74, v74, v204
	v_add_f32_e32 v75, v75, v205
	s_waitcnt vmcnt(12)
	v_add_f32_e32 v76, v76, v206
	v_add_f32_e32 v77, v77, v207
	v_add_f32_e32 v78, v78, v208
	v_add_f32_e32 v79, v79, v209
	s_waitcnt vmcnt(11)
; template <int EPI> ...
;     ...
;     } else if (EPI == EPI_RES) {
; #pragma unroll
;       for (int i = 0; i < 16; i++) {
;         const int rl = rbase + (i & 3) + 8 * (i >> 2);
;         const int row = m0 + rl;
;         float v0 = acc0[i], v1 = acc1[i];
;         xf[(size_t)row * 1024 + c0] = v0;
;         xf[(size_t)row * 1024 + c1] = v1;
;         outb[(size_t)row * 1024 + c0] = f2bf(v0);
;         outb[(size_t)row * 1024 + c1] = f2bf(v1);
;         float s = hsum32(v0 * v0 + v1 * v1);
;         if ((lane & 31) == 0) part[(size_t)row * 16 + nt * 2 + wn] = s;
;       }
	v_add_f32_e32 v80, v80, v210
	v_add_f32_e32 v81, v81, v211
	v_add_f32_e32 v82, v82, v212
	v_add_f32_e32 v83, v83, v213
	s_waitcnt vmcnt(10)
	v_add_f32_e32 v84, v84, v214
	v_add_f32_e32 v85, v85, v215
	v_add_f32_e32 v86, v86, v216
	v_add_f32_e32 v87, v87, v217
	s_waitcnt vmcnt(9)
	v_add_f32_e32 v88, v88, v218
	v_add_f32_e32 v89, v89, v219
	v_add_f32_e32 v90, v90, v220
	v_add_f32_e32 v91, v91, v221
	s_waitcnt vmcnt(8)
	v_add_f32_e32 v92, v92, v222
	v_add_f32_e32 v93, v93, v223
	v_add_f32_e32 v94, v94, v224
	v_add_f32_e32 v95, v95, v225
	s_waitcnt vmcnt(7)
	v_add_f32_e32 v96, v96, v130
	v_add_f32_e32 v97, v97, v131
	v_add_f32_e32 v98, v98, v132
	v_add_f32_e32 v99, v99, v133
	s_waitcnt vmcnt(6)
	v_add_f32_e32 v100, v100, v134
	v_add_f32_e32 v101, v101, v135
	v_add_f32_e32 v102, v102, v136
	v_add_f32_e32 v103, v103, v137
	s_waitcnt vmcnt(5)
	v_add_f32_e32 v104, v104, v138
	v_add_f32_e32 v105, v105, v139
	v_add_f32_e32 v106, v106, v140
	v_add_f32_e32 v107, v107, v141
	s_waitcnt vmcnt(4)
	v_add_f32_e32 v108, v108, v142
	v_add_f32_e32 v109, v109, v143
	v_add_f32_e32 v110, v110, v144
	v_add_f32_e32 v111, v111, v145
	s_waitcnt vmcnt(3)
	v_add_f32_e32 v112, v112, v146
	v_add_f32_e32 v113, v113, v147
	v_add_f32_e32 v114, v114, v148
	v_add_f32_e32 v115, v115, v149
	s_waitcnt vmcnt(2)
	v_add_f32_e32 v116, v116, v150
	v_add_f32_e32 v117, v117, v151
	v_add_f32_e32 v118, v118, v152
	v_add_f32_e32 v119, v119, v153
	s_waitcnt vmcnt(1)
	v_add_f32_e32 v120, v120, v154
	v_add_f32_e32 v121, v121, v155
	v_add_f32_e32 v122, v122, v156
	v_add_f32_e32 v123, v123, v157
	s_waitcnt vmcnt(0)
	v_add_f32_e32 v124, v124, v158
	v_add_f32_e32 v125, v125, v159
	v_add_f32_e32 v126, v126, v160
	v_add_f32_e32 v127, v127, v161
	global_store_dwordx4 v243, v[0:3], s[94:95]
	v_mul_f32_e32 v234, v0, v0
	v_fmac_f32_e32 v234, v1, v1
	v_fmac_f32_e32 v234, v2, v2
	v_fmac_f32_e32 v234, v3, v3
	global_store_dwordx4 v243, v[4:7], s[94:95] offset:64
	v_fmac_f32_e32 v234, v4, v4
	v_fmac_f32_e32 v234, v5, v5
	v_fmac_f32_e32 v234, v6, v6
	v_fmac_f32_e32 v234, v7, v7
	global_store_dwordx4 v243, v[8:11], s[94:95] offset:128
	v_fmac_f32_e32 v234, v8, v8
	v_fmac_f32_e32 v234, v9, v9
	v_fmac_f32_e32 v234, v10, v10
	v_fmac_f32_e32 v234, v11, v11
	global_store_dwordx4 v243, v[12:15], s[94:95] offset:192
	v_fmac_f32_e32 v234, v12, v12
	v_fmac_f32_e32 v234, v13, v13
	v_fmac_f32_e32 v234, v14, v14
	v_fmac_f32_e32 v234, v15, v15
	global_store_dwordx4 v243, v[16:19], s[94:95] offset:256
	v_fmac_f32_e32 v234, v16, v16
	v_fmac_f32_e32 v234, v17, v17
	v_fmac_f32_e32 v234, v18, v18
	v_fmac_f32_e32 v234, v19, v19
	global_store_dwordx4 v243, v[20:23], s[94:95] offset:320
	v_fmac_f32_e32 v234, v20, v20
	v_fmac_f32_e32 v234, v21, v21
	v_fmac_f32_e32 v234, v22, v22
	v_fmac_f32_e32 v234, v23, v23
	global_store_dwordx4 v243, v[24:27], s[94:95] offset:384
	v_fmac_f32_e32 v234, v24, v24
	v_fmac_f32_e32 v234, v25, v25
	v_fmac_f32_e32 v234, v26, v26
	v_fmac_f32_e32 v234, v27, v27
	global_store_dwordx4 v243, v[28:31], s[94:95] offset:448
	v_fmac_f32_e32 v234, v28, v28
	v_fmac_f32_e32 v234, v29, v29
	v_fmac_f32_e32 v234, v30, v30
	v_fmac_f32_e32 v234, v31, v31
	global_store_dwordx4 v244, v[32:35], s[94:95]
	v_mul_f32_e32 v235, v32, v32
	v_fmac_f32_e32 v235, v33, v33
	v_fmac_f32_e32 v235, v34, v34
	v_fmac_f32_e32 v235, v35, v35
	global_store_dwordx4 v244, v[36:39], s[94:95] offset:64
	v_fmac_f32_e32 v235, v36, v36
	v_fmac_f32_e32 v235, v37, v37
	v_fmac_f32_e32 v235, v38, v38
	v_fmac_f32_e32 v235, v39, v39
	global_store_dwordx4 v244, v[40:43], s[94:95] offset:128
	v_fmac_f32_e32 v235, v40, v40
	v_fmac_f32_e32 v235, v41, v41
	v_fmac_f32_e32 v235, v42, v42
	v_fmac_f32_e32 v235, v43, v43
	global_store_dwordx4 v244, v[44:47], s[94:95] offset:192
	v_fmac_f32_e32 v235, v44, v44
	v_fmac_f32_e32 v235, v45, v45
	v_fmac_f32_e32 v235, v46, v46
	v_fmac_f32_e32 v235, v47, v47
	global_store_dwordx4 v244, v[48:51], s[94:95] offset:256
	v_fmac_f32_e32 v235, v48, v48
	v_fmac_f32_e32 v235, v49, v49
	v_fmac_f32_e32 v235, v50, v50
	v_fmac_f32_e32 v235, v51, v51
	global_store_dwordx4 v244, v[52:55], s[94:95] offset:320
	v_fmac_f32_e32 v235, v52, v52
	v_fmac_f32_e32 v235, v53, v53
	v_fmac_f32_e32 v235, v54, v54
	v_fmac_f32_e32 v235, v55, v55
	global_store_dwordx4 v244, v[56:59], s[94:95] offset:384
	v_fmac_f32_e32 v235, v56, v56
	v_fmac_f32_e32 v235, v57, v57
	v_fmac_f32_e32 v235, v58, v58
	v_fmac_f32_e32 v235, v59, v59
	global_store_dwordx4 v244, v[60:63], s[94:95] offset:448
	v_fmac_f32_e32 v235, v60, v60
	v_fmac_f32_e32 v235, v61, v61
	v_fmac_f32_e32 v235, v62, v62
	v_fmac_f32_e32 v235, v63, v63
	global_store_dwordx4 v245, v[64:67], s[94:95]
	v_mul_f32_e32 v236, v64, v64
	v_fmac_f32_e32 v236, v65, v65
	v_fmac_f32_e32 v236, v66, v66
	v_fmac_f32_e32 v236, v67, v67
	global_store_dwordx4 v245, v[68:71], s[94:95] offset:64
	v_fmac_f32_e32 v236, v68, v68
	v_fmac_f32_e32 v236, v69, v69
	v_fmac_f32_e32 v236, v70, v70
	v_fmac_f32_e32 v236, v71, v71
	global_store_dwordx4 v245, v[72:75], s[94:95] offset:128
	v_fmac_f32_e32 v236, v72, v72
	v_fmac_f32_e32 v236, v73, v73
	v_fmac_f32_e32 v236, v74, v74
	v_fmac_f32_e32 v236, v75, v75
	global_store_dwordx4 v245, v[76:79], s[94:95] offset:192
	v_fmac_f32_e32 v236, v76, v76
	v_fmac_f32_e32 v236, v77, v77
	v_fmac_f32_e32 v236, v78, v78
	v_fmac_f32_e32 v236, v79, v79
	global_store_dwordx4 v245, v[80:83], s[94:95] offset:256
	v_fmac_f32_e32 v236, v80, v80
	v_fmac_f32_e32 v236, v81, v81
	v_fmac_f32_e32 v236, v82, v82
	v_fmac_f32_e32 v236, v83, v83
	global_store_dwordx4 v245, v[84:87], s[94:95] offset:320
	v_fmac_f32_e32 v236, v84, v84
	v_fmac_f32_e32 v236, v85, v85
	v_fmac_f32_e32 v236, v86, v86
; template <int EPI> ...
;     ...
;         xf[(size_t)row * 1024 + c0] = v0;
;         xf[(size_t)row * 1024 + c1] = v1;
;         outb[(size_t)row * 1024 + c0] = f2bf(v0);
;         outb[(size_t)row * 1024 + c1] = f2bf(v1);
;         float s = hsum32(v0 * v0 + v1 * v1);
;         if ((lane & 31) == 0) part[(size_t)row * 16 + nt * 2 + wn] = s;
	v_fmac_f32_e32 v236, v87, v87
	global_store_dwordx4 v245, v[88:91], s[94:95] offset:384
	v_fmac_f32_e32 v236, v88, v88
	v_fmac_f32_e32 v236, v89, v89
	v_fmac_f32_e32 v236, v90, v90
	v_fmac_f32_e32 v236, v91, v91
	global_store_dwordx4 v245, v[92:95], s[94:95] offset:448
	v_fmac_f32_e32 v236, v92, v92
	v_fmac_f32_e32 v236, v93, v93
	v_fmac_f32_e32 v236, v94, v94
	v_fmac_f32_e32 v236, v95, v95
	global_store_dwordx4 v246, v[96:99], s[94:95]
	v_mul_f32_e32 v237, v96, v96
	v_fmac_f32_e32 v237, v97, v97
	v_fmac_f32_e32 v237, v98, v98
	v_fmac_f32_e32 v237, v99, v99
	global_store_dwordx4 v246, v[100:103], s[94:95] offset:64
	v_fmac_f32_e32 v237, v100, v100
	v_fmac_f32_e32 v237, v101, v101
	v_fmac_f32_e32 v237, v102, v102
	v_fmac_f32_e32 v237, v103, v103
	global_store_dwordx4 v246, v[104:107], s[94:95] offset:128
	v_fmac_f32_e32 v237, v104, v104
	v_fmac_f32_e32 v237, v105, v105
	v_fmac_f32_e32 v237, v106, v106
	v_fmac_f32_e32 v237, v107, v107
	global_store_dwordx4 v246, v[108:111], s[94:95] offset:192
	v_fmac_f32_e32 v237, v108, v108
	v_fmac_f32_e32 v237, v109, v109
	v_fmac_f32_e32 v237, v110, v110
	v_fmac_f32_e32 v237, v111, v111
	global_store_dwordx4 v246, v[112:115], s[94:95] offset:256
	v_fmac_f32_e32 v237, v112, v112
	v_fmac_f32_e32 v237, v113, v113
	v_fmac_f32_e32 v237, v114, v114
	v_fmac_f32_e32 v237, v115, v115
	global_store_dwordx4 v246, v[116:119], s[94:95] offset:320
	v_fmac_f32_e32 v237, v116, v116
	v_fmac_f32_e32 v237, v117, v117
	v_fmac_f32_e32 v237, v118, v118
	v_fmac_f32_e32 v237, v119, v119
	global_store_dwordx4 v246, v[120:123], s[94:95] offset:384
	v_fmac_f32_e32 v237, v120, v120
	v_fmac_f32_e32 v237, v121, v121
	v_fmac_f32_e32 v237, v122, v122
	v_fmac_f32_e32 v237, v123, v123
	global_store_dwordx4 v246, v[124:127], s[94:95] offset:448
	v_fmac_f32_e32 v237, v124, v124
	v_fmac_f32_e32 v237, v125, v125
	v_fmac_f32_e32 v237, v126, v126
	v_fmac_f32_e32 v237, v127, v127
	s_cmp_eq_u32 s101, 19
	s_cbranch_scc1 .Lgc_res_nobf
	v_cvt_pk_bf16_f32 v0, v0, v1
	v_cvt_pk_bf16_f32 v1, v2, v3
	v_cvt_pk_bf16_f32 v2, v4, v5
	v_cvt_pk_bf16_f32 v3, v6, v7
	s_nop 1
	v_permlane16_swap_b32_e32 v0, v2
	v_permlane16_swap_b32_e32 v1, v3
	global_store_dwordx4 v230, v[0:3], s[22:23]
	v_cvt_pk_bf16_f32 v8, v8, v9
	v_cvt_pk_bf16_f32 v9, v10, v11
	v_cvt_pk_bf16_f32 v10, v12, v13
	v_cvt_pk_bf16_f32 v11, v14, v15
	s_nop 1
	v_permlane16_swap_b32_e32 v8, v10
	v_permlane16_swap_b32_e32 v9, v11
	global_store_dwordx4 v230, v[8:11], s[22:23] offset:64
	v_cvt_pk_bf16_f32 v16, v16, v17
	v_cvt_pk_bf16_f32 v17, v18, v19
	v_cvt_pk_bf16_f32 v18, v20, v21
	v_cvt_pk_bf16_f32 v19, v22, v23
	s_nop 1
	v_permlane16_swap_b32_e32 v16, v18
	v_permlane16_swap_b32_e32 v17, v19
	global_store_dwordx4 v230, v[16:19], s[22:23] offset:128
	v_cvt_pk_bf16_f32 v24, v24, v25
	v_cvt_pk_bf16_f32 v25, v26, v27
	v_cvt_pk_bf16_f32 v26, v28, v29
	v_cvt_pk_bf16_f32 v27, v30, v31
	s_nop 1
	v_permlane16_swap_b32_e32 v24, v26
	v_permlane16_swap_b32_e32 v25, v27
	global_store_dwordx4 v230, v[24:27], s[22:23] offset:192
	v_cvt_pk_bf16_f32 v32, v32, v33
	v_cvt_pk_bf16_f32 v33, v34, v35
	v_cvt_pk_bf16_f32 v34, v36, v37
	v_cvt_pk_bf16_f32 v35, v38, v39
	s_nop 1
	v_permlane16_swap_b32_e32 v32, v34
	v_permlane16_swap_b32_e32 v33, v35
	global_store_dwordx4 v231, v[32:35], s[22:23]
	v_cvt_pk_bf16_f32 v40, v40, v41
	v_cvt_pk_bf16_f32 v41, v42, v43
	v_cvt_pk_bf16_f32 v42, v44, v45
	v_cvt_pk_bf16_f32 v43, v46, v47
	s_nop 1
	v_permlane16_swap_b32_e32 v40, v42
	v_permlane16_swap_b32_e32 v41, v43
	global_store_dwordx4 v231, v[40:43], s[22:23] offset:64
	v_cvt_pk_bf16_f32 v48, v48, v49
	v_cvt_pk_bf16_f32 v49, v50, v51
	v_cvt_pk_bf16_f32 v50, v52, v53
	v_cvt_pk_bf16_f32 v51, v54, v55
	s_nop 1
	v_permlane16_swap_b32_e32 v48, v50
	v_permlane16_swap_b32_e32 v49, v51
	global_store_dwordx4 v231, v[48:51], s[22:23] offset:128
	v_cvt_pk_bf16_f32 v56, v56, v57
	v_cvt_pk_bf16_f32 v57, v58, v59
	v_cvt_pk_bf16_f32 v58, v60, v61
	v_cvt_pk_bf16_f32 v59, v62, v63
	s_nop 1
	v_permlane16_swap_b32_e32 v56, v58
	v_permlane16_swap_b32_e32 v57, v59
	global_store_dwordx4 v231, v[56:59], s[22:23] offset:192
	v_cvt_pk_bf16_f32 v64, v64, v65
	v_cvt_pk_bf16_f32 v65, v66, v67
	v_cvt_pk_bf16_f32 v66, v68, v69
	v_cvt_pk_bf16_f32 v67, v70, v71
	s_nop 1
	v_permlane16_swap_b32_e32 v64, v66
	v_permlane16_swap_b32_e32 v65, v67
	global_store_dwordx4 v232, v[64:67], s[22:23]
	v_cvt_pk_bf16_f32 v72, v72, v73
	v_cvt_pk_bf16_f32 v73, v74, v75
	v_cvt_pk_bf16_f32 v74, v76, v77
	v_cvt_pk_bf16_f32 v75, v78, v79
	s_nop 1
	v_permlane16_swap_b32_e32 v72, v74
	v_permlane16_swap_b32_e32 v73, v75
	global_store_dwordx4 v232, v[72:75], s[22:23] offset:64
	v_cvt_pk_bf16_f32 v80, v80, v81
	v_cvt_pk_bf16_f32 v81, v82, v83
	v_cvt_pk_bf16_f32 v82, v84, v85
	v_cvt_pk_bf16_f32 v83, v86, v87
	s_nop 1
	v_permlane16_swap_b32_e32 v80, v82
	v_permlane16_swap_b32_e32 v81, v83
	global_store_dwordx4 v232, v[80:83], s[22:23] offset:128
	v_cvt_pk_bf16_f32 v88, v88, v89
	v_cvt_pk_bf16_f32 v89, v90, v91
	v_cvt_pk_bf16_f32 v90, v92, v93
	v_cvt_pk_bf16_f32 v91, v94, v95
	s_nop 1
	v_permlane16_swap_b32_e32 v88, v90
	v_permlane16_swap_b32_e32 v89, v91
	global_store_dwordx4 v232, v[88:91], s[22:23] offset:192
	v_cvt_pk_bf16_f32 v96, v96, v97
	v_cvt_pk_bf16_f32 v97, v98, v99
	v_cvt_pk_bf16_f32 v98, v100, v101
	v_cvt_pk_bf16_f32 v99, v102, v103
	s_nop 1
	v_permlane16_swap_b32_e32 v96, v98
	v_permlane16_swap_b32_e32 v97, v99
	global_store_dwordx4 v233, v[96:99], s[22:23]
	v_cvt_pk_bf16_f32 v104, v104, v105
	v_cvt_pk_bf16_f32 v105, v106, v107
	v_cvt_pk_bf16_f32 v106, v108, v109
	v_cvt_pk_bf16_f32 v107, v110, v111
	s_nop 1
	v_permlane16_swap_b32_e32 v104, v106
	v_permlane16_swap_b32_e32 v105, v107
	global_store_dwordx4 v233, v[104:107], s[22:23] offset:64
	v_cvt_pk_bf16_f32 v112, v112, v113
	v_cvt_pk_bf16_f32 v113, v114, v115
	v_cvt_pk_bf16_f32 v114, v116, v117
	v_cvt_pk_bf16_f32 v115, v118, v119
	s_nop 1
	v_permlane16_swap_b32_e32 v112, v114
	v_permlane16_swap_b32_e32 v113, v115
	global_store_dwordx4 v233, v[112:115], s[22:23] offset:128
	v_cvt_pk_bf16_f32 v120, v120, v121
	v_cvt_pk_bf16_f32 v121, v122, v123
	v_cvt_pk_bf16_f32 v122, v124, v125
	v_cvt_pk_bf16_f32 v123, v126, v127
	s_nop 1
	v_permlane16_swap_b32_e32 v120, v122
	v_permlane16_swap_b32_e32 v121, v123
	global_store_dwordx4 v233, v[120:123], s[22:23] offset:192
; __device__ __forceinline__ float hsum32(float v) {
;   v = row16sum(v);
;   return v + __shfl_xor(v, 16);
; }
; template <int EPI> ...
;     ...
;         float s = hsum32(v0 * v0 + v1 * v1);
;         if ((lane & 31) == 0) part[(size_t)row * 16 + nt * 2 + wn] = s;
.Lgc_res_nobf:
	v_mov_b32_e32 v238, v234
	v_mov_b32_e32 v239, v235
	v_mov_b32_e32 v240, v236
	v_mov_b32_e32 v241, v237
	s_nop 1
	v_permlane16_swap_b32_e32 v238, v234
	v_permlane16_swap_b32_e32 v239, v235
	v_permlane16_swap_b32_e32 v240, v236
	v_permlane16_swap_b32_e32 v241, v237
	v_add_f32_e32 v234, v234, v238
	v_add_f32_e32 v235, v235, v239
	v_add_f32_e32 v236, v236, v240
	v_add_f32_e32 v237, v237, v241
	v_mov_b32_e32 v238, v234
	v_mov_b32_e32 v239, v235
	v_mov_b32_e32 v240, v236
	v_mov_b32_e32 v241, v237
	s_nop 1
	v_permlane32_swap_b32_e32 v238, v234
	v_permlane32_swap_b32_e32 v239, v235
	v_permlane32_swap_b32_e32 v240, v236
	v_permlane32_swap_b32_e32 v241, v237
	v_add_f32_e32 v234, v234, v238
	v_add_f32_e32 v235, v235, v239
	v_add_f32_e32 v236, v236, v240
	v_add_f32_e32 v237, v237, v241
	v_mov_b32_e32 v238, v234
	v_mov_b32_e32 v239, 0
	global_store_dwordx2 v247, v[238:239], s[14:15]
	s_nop 1
	v_mov_b32_e32 v238, v235
	v_mov_b32_e32 v239, 0
	global_store_dwordx2 v247, v[238:239], s[14:15] offset:1024
	s_nop 1
	v_mov_b32_e32 v238, v236
	v_mov_b32_e32 v239, 0
	global_store_dwordx2 v247, v[238:239], s[14:15] offset:2048
	s_nop 1
	v_mov_b32_e32 v238, v237
	v_mov_b32_e32 v239, 0
	global_store_dwordx2 v247, v[238:239], s[14:15] offset:3072
	s_nop 1
	s_branch .Lgc_next
